# attention: the four PV MFMAs of a key half issued back to back behind one LDS wait (removed the leftover issue slots and per-MFMA waits between them)
# speedup vs baseline: 1.0009x; 1.0009x over previous
; __device__ __forceinline__ unsigned cvt_pk_bf16(float lo, float hi) { const f32x2c_ v = {lo, hi}; const bf16x2c_ b = __builtin_convertvector(v, bf16x2c_); return __builtin_bit_cast(unsigned, b); }
; #define LAS __attribute__((address_space(3)))
; #define MFMA32(a, b, c) __builtin_amdgcn_mfma_f32_32x32x16_bf16(a, b, c, 0, 0, 0)
; __device__ __forceinline__ void attn_unit(int bh, int qb, const bf16_t* QKV, const bf16_t* KF, const float* cstab, const float* qg, bf16_t* MIX, LAS unsigned char* lds) {
;     ...
;             float ps = 0.f;
; #pragma unroll
;             for (int r = 0; r < 16; ++r) { p[r] = __builtin_amdgcn_exp2f(p[r]); ps += p[r]; }
;             lrun += ps;
;             u32x4 w0, w1;
; #pragma unroll
;             for (int k = 0; k < 4; ++k) { w0[k] = cvt_pk_bf16(p[2 * k], p[2 * k + 1]); w1[k] = cvt_pk_bf16(p[8 + 2 * k], p[8 + 2 * k + 1]); }
;             const bf16x8 pb0 = __builtin_bit_cast(bf16x8, w0), pb1 = __builtin_bit_cast(bf16x8, w1);
;             const LAS unsigned char* vp = buf + vtb + (32 * kb) * VROW;
; #pragma unroll
;             for (int db = 0; db < 2; ++db) {
;                 const v4i16_t a0 = __builtin_amdgcn_ds_read_tr16_b64_v4i16((LAS v4i16_t*)(vp + db * 64));
;                 const v4i16_t a1 = __builtin_amdgcn_ds_read_tr16_b64_v4i16((LAS v4i16_t*)(vp + db * 64 + 8 * VROW));
;                 const v4i16_t c0 = __builtin_amdgcn_ds_read_tr16_b64_v4i16((LAS v4i16_t*)(vp + db * 64 + 16 * VROW));
;                 const v4i16_t c1 = __builtin_amdgcn_ds_read_tr16_b64_v4i16((LAS v4i16_t*)(vp + db * 64 + 24 * VROW));
;                 const bf16x8 va = {a0[0], a0[1], a0[2], a0[3], a1[0], a1[1], a1[2], a1[3]}, vc = {c0[0], c0[1], c0[2], c0[3], c1[0], c1[1], c1[2], c1[3]};
;                 __builtin_amdgcn_s_setprio(1);
;                 if (db == 0) { o0 = MFMA32(va, pb0, o0); o0 = MFMA32(vc, pb1, o0); }
;                 else { o1 = MFMA32(va, pb0, o1); o1 = MFMA32(vc, pb1, o1); }
;                 __builtin_amdgcn_s_setprio(0);
;             }
.LBB0_1066:
	v_exp_f32_e32 v48, v48
	v_exp_f32_e32 v49, v49
	v_exp_f32_e32 v50, v50
	v_exp_f32_e32 v51, v51
	v_exp_f32_e32 v122, v52
	v_add_f32_e32 v121, v49, v48
	v_add_f32_e32 v121, v50, v121
	v_add_f32_e32 v121, v51, v121
	v_add_f32_e32 v52, v122, v121
	v_exp_f32_e32 v121, v53
	v_exp_f32_e32 v123, v54
	v_exp_f32_e32 v55, v55
	v_exp_f32_e32 v53, v56
	v_add_f32_e32 v52, v121, v52
	v_exp_f32_e32 v54, v57
	v_add_f32_e32 v52, v123, v52
	v_exp_f32_e32 v56, v58
	v_add_f32_e32 v52, v55, v52
	v_exp_f32_e32 v57, v59
	v_add_f32_e32 v52, v53, v52
	v_exp_f32_e32 v58, v60
	v_add_f32_e32 v52, v54, v52
	v_exp_f32_e32 v59, v61
	v_add_f32_e32 v52, v56, v52
	v_exp_f32_e32 v60, v62
	v_add_f32_e32 v52, v57, v52
	v_exp_f32_e32 v61, v63
	v_add_f32_e32 v52, v58, v52
	v_add_f32_e32 v52, v59, v52
	v_add_f32_e32 v52, v60, v52
	v_cvt_pk_bf16_f32 v48, v48, v49
	v_cvt_pk_bf16_f32 v49, v50, v51
	v_cvt_pk_bf16_f32 v50, v122, v121
	v_add_f32_e32 v124, v61, v52
	v_cvt_pk_bf16_f32 v52, v53, v54
	v_cvt_pk_bf16_f32 v53, v56, v57
	v_cvt_pk_bf16_f32 v54, v58, v59
	v_cvt_pk_bf16_f32 v51, v123, v55
	v_cvt_pk_bf16_f32 v55, v60, v61
	s_nop 0
	s_waitcnt lgkmcnt(6)
	v_mfma_f32_32x32x16_bf16 v[0:15], v[156:159], v[48:51], v[0:15]
	v_mfma_f32_32x32x16_bf16 v[0:15], v[160:163], v[52:55], v[0:15]
	v_mfma_f32_32x32x16_bf16 v[16:31], v[164:167], v[48:51], v[16:31]
	v_mfma_f32_32x32x16_bf16 v[16:31], v[168:171], v[52:55], v[16:31]
	s_nop 0
	v_add_f32_e32 v107, v107, v124
	s_add_i32 s44, s43, 0x60
	s_cmp_gt_i32 s44, s2
	s_cbranch_scc0 .LBB0_1069

; __device__ __forceinline__ unsigned cvt_pk_bf16(float lo, float hi) { const f32x2c_ v = {lo, hi}; const bf16x2c_ b = __builtin_convertvector(v, bf16x2c_); return __builtin_bit_cast(unsigned, b); }
; #define LAS __attribute__((address_space(3)))
; #define MFMA32(a, b, c) __builtin_amdgcn_mfma_f32_32x32x16_bf16(a, b, c, 0, 0, 0)
; __device__ __forceinline__ void attn_unit(int bh, int qb, const bf16_t* QKV, const bf16_t* KF, const float* cstab, const float* qg, bf16_t* MIX, LAS unsigned char* lds) {
;     ...
;             float ps = 0.f;
; #pragma unroll
;             for (int r = 0; r < 16; ++r) { p[r] = __builtin_amdgcn_exp2f(p[r]); ps += p[r]; }
;             lrun += ps;
;             u32x4 w0, w1;
; #pragma unroll
;             for (int k = 0; k < 4; ++k) { w0[k] = cvt_pk_bf16(p[2 * k], p[2 * k + 1]); w1[k] = cvt_pk_bf16(p[8 + 2 * k], p[8 + 2 * k + 1]); }
;             const bf16x8 pb0 = __builtin_bit_cast(bf16x8, w0), pb1 = __builtin_bit_cast(bf16x8, w1);
;             const LAS unsigned char* vp = buf + vtb + (32 * kb) * VROW;
; #pragma unroll
;             for (int db = 0; db < 2; ++db) {
;                 const v4i16_t a0 = __builtin_amdgcn_ds_read_tr16_b64_v4i16((LAS v4i16_t*)(vp + db * 64));
;                 const v4i16_t a1 = __builtin_amdgcn_ds_read_tr16_b64_v4i16((LAS v4i16_t*)(vp + db * 64 + 8 * VROW));
;                 const v4i16_t c0 = __builtin_amdgcn_ds_read_tr16_b64_v4i16((LAS v4i16_t*)(vp + db * 64 + 16 * VROW));
;                 const v4i16_t c1 = __builtin_amdgcn_ds_read_tr16_b64_v4i16((LAS v4i16_t*)(vp + db * 64 + 24 * VROW));
;                 const bf16x8 va = {a0[0], a0[1], a0[2], a0[3], a1[0], a1[1], a1[2], a1[3]}, vc = {c0[0], c0[1], c0[2], c0[3], c1[0], c1[1], c1[2], c1[3]};
;                 __builtin_amdgcn_s_setprio(1);
;                 if (db == 0) { o0 = MFMA32(va, pb0, o0); o0 = MFMA32(vc, pb1, o0); }
;                 else { o1 = MFMA32(va, pb0, o1); o1 = MFMA32(vc, pb1, o1); }
;                 __builtin_amdgcn_s_setprio(0);
;             }
.LBB0_1073:
	v_exp_f32_e32 v48, v48
	v_exp_f32_e32 v49, v49
	v_exp_f32_e32 v50, v50
	v_exp_f32_e32 v51, v51
	v_exp_f32_e32 v121, v52
	v_add_f32_e32 v120, v49, v48
	v_add_f32_e32 v120, v50, v120
	v_add_f32_e32 v120, v51, v120
	v_add_f32_e32 v52, v121, v120
	v_exp_f32_e32 v120, v53
	v_exp_f32_e32 v122, v54
	v_exp_f32_e32 v55, v55
	v_exp_f32_e32 v53, v56
	v_add_f32_e32 v52, v120, v52
	v_exp_f32_e32 v54, v57
	v_add_f32_e32 v52, v122, v52
	v_exp_f32_e32 v56, v58
	v_add_f32_e32 v52, v55, v52
	v_exp_f32_e32 v57, v59
	v_add_f32_e32 v52, v53, v52
	v_exp_f32_e32 v58, v60
	v_add_f32_e32 v52, v54, v52
	v_exp_f32_e32 v59, v61
	v_add_f32_e32 v52, v56, v52
	v_exp_f32_e32 v60, v62
	v_add_f32_e32 v52, v57, v52
	v_exp_f32_e32 v61, v63
	v_add_f32_e32 v52, v58, v52
	v_add_f32_e32 v52, v59, v52
	v_add_f32_e32 v52, v60, v52
	v_add_f32_e32 v123, v61, v52
	v_cvt_pk_bf16_f32 v48, v48, v49
	v_cvt_pk_bf16_f32 v52, v53, v54
	v_cvt_pk_bf16_f32 v49, v50, v51
	v_cvt_pk_bf16_f32 v53, v56, v57
	v_cvt_pk_bf16_f32 v54, v58, v59
	v_cvt_pk_bf16_f32 v51, v122, v55
	v_cvt_pk_bf16_f32 v55, v60, v61
	v_cvt_pk_bf16_f32 v50, v121, v120
	s_nop 0
	s_waitcnt lgkmcnt(0)
	v_mfma_f32_32x32x16_bf16 v[0:15], v[156:159], v[48:51], v[0:15]
	v_mfma_f32_32x32x16_bf16 v[0:15], v[160:163], v[52:55], v[0:15]
	v_mfma_f32_32x32x16_bf16 v[16:31], v[164:167], v[48:51], v[16:31]
	v_mfma_f32_32x32x16_bf16 v[16:31], v[168:171], v[52:55], v[16:31]
	s_nop 0
	v_add_f32_e32 v107, v107, v123
	s_andn2_b64 vcc, exec, s[4:5]
	s_cbranch_vccnz .LBB0_1077

; __device__ __forceinline__ unsigned cvt_pk_bf16(float lo, float hi) { const f32x2c_ v = {lo, hi}; const bf16x2c_ b = __builtin_convertvector(v, bf16x2c_); return __builtin_bit_cast(unsigned, b); }
; #define LAS __attribute__((address_space(3)))
; #define MFMA32(a, b, c) __builtin_amdgcn_mfma_f32_32x32x16_bf16(a, b, c, 0, 0, 0)
; __device__ __forceinline__ void attn_unit(int bh, int qb, const bf16_t* QKV, const bf16_t* KF, const float* cstab, const float* qg, bf16_t* MIX, LAS unsigned char* lds) {
;     ...
;             float ps = 0.f;
; #pragma unroll
;             for (int r = 0; r < 16; ++r) { p[r] = __builtin_amdgcn_exp2f(p[r]); ps += p[r]; }
;             lrun += ps;
;             u32x4 w0, w1;
; #pragma unroll
;             for (int k = 0; k < 4; ++k) { w0[k] = cvt_pk_bf16(p[2 * k], p[2 * k + 1]); w1[k] = cvt_pk_bf16(p[8 + 2 * k], p[8 + 2 * k + 1]); }
;             const bf16x8 pb0 = __builtin_bit_cast(bf16x8, w0), pb1 = __builtin_bit_cast(bf16x8, w1);
;             const LAS unsigned char* vp = buf + vtb + (32 * kb) * VROW;
; #pragma unroll
;             for (int db = 0; db < 2; ++db) {
;                 const v4i16_t a0 = __builtin_amdgcn_ds_read_tr16_b64_v4i16((LAS v4i16_t*)(vp + db * 64));
;                 const v4i16_t a1 = __builtin_amdgcn_ds_read_tr16_b64_v4i16((LAS v4i16_t*)(vp + db * 64 + 8 * VROW));
;                 const v4i16_t c0 = __builtin_amdgcn_ds_read_tr16_b64_v4i16((LAS v4i16_t*)(vp + db * 64 + 16 * VROW));
;                 const v4i16_t c1 = __builtin_amdgcn_ds_read_tr16_b64_v4i16((LAS v4i16_t*)(vp + db * 64 + 24 * VROW));
;                 const bf16x8 va = {a0[0], a0[1], a0[2], a0[3], a1[0], a1[1], a1[2], a1[3]}, vc = {c0[0], c0[1], c0[2], c0[3], c1[0], c1[1], c1[2], c1[3]};
;                 __builtin_amdgcn_s_setprio(1);
;                 if (db == 0) { o0 = MFMA32(va, pb0, o0); o0 = MFMA32(vc, pb1, o0); }
;                 else { o1 = MFMA32(va, pb0, o1); o1 = MFMA32(vc, pb1, o1); }
;                 __builtin_amdgcn_s_setprio(0);
;             }
.LBB0_1107:
	v_exp_f32_e32 v48, v48
	v_exp_f32_e32 v49, v49
	v_exp_f32_e32 v50, v50
	v_exp_f32_e32 v51, v51
	v_exp_f32_e32 v122, v52
	v_add_f32_e32 v121, v49, v48
	v_add_f32_e32 v121, v50, v121
	v_add_f32_e32 v121, v51, v121
	v_add_f32_e32 v52, v122, v121
	v_exp_f32_e32 v121, v53
	v_exp_f32_e32 v123, v54
	v_exp_f32_e32 v55, v55
	v_exp_f32_e32 v53, v56
	v_add_f32_e32 v52, v121, v52
	v_exp_f32_e32 v54, v57
	v_add_f32_e32 v52, v123, v52
	v_exp_f32_e32 v56, v58
	v_add_f32_e32 v52, v55, v52
	v_exp_f32_e32 v57, v59
	v_add_f32_e32 v52, v53, v52
	v_exp_f32_e32 v58, v60
	v_add_f32_e32 v52, v54, v52
	v_exp_f32_e32 v59, v61
	v_add_f32_e32 v52, v56, v52
	v_exp_f32_e32 v60, v62
	v_add_f32_e32 v52, v57, v52
	v_exp_f32_e32 v61, v63
	v_add_f32_e32 v52, v58, v52
	v_add_f32_e32 v52, v59, v52
	v_add_f32_e32 v52, v60, v52
	v_cvt_pk_bf16_f32 v48, v48, v49
	v_cvt_pk_bf16_f32 v49, v50, v51
	v_cvt_pk_bf16_f32 v50, v122, v121
	v_add_f32_e32 v124, v61, v52
	v_cvt_pk_bf16_f32 v52, v53, v54
	v_cvt_pk_bf16_f32 v53, v56, v57
	v_cvt_pk_bf16_f32 v54, v58, v59
	v_cvt_pk_bf16_f32 v51, v123, v55
	v_cvt_pk_bf16_f32 v55, v60, v61
	s_nop 0
	s_waitcnt lgkmcnt(6)
	v_mfma_f32_32x32x16_bf16 v[0:15], v[156:159], v[48:51], v[0:15]
	v_mfma_f32_32x32x16_bf16 v[0:15], v[160:163], v[52:55], v[0:15]
	v_mfma_f32_32x32x16_bf16 v[16:31], v[164:167], v[48:51], v[16:31]
	v_mfma_f32_32x32x16_bf16 v[16:31], v[168:171], v[52:55], v[16:31]
	s_nop 0
	v_add_f32_e32 v107, v107, v124
	s_add_i32 s30, s29, 0x60
	s_cmp_gt_i32 s30, s18
	s_cbranch_scc0 .LBB0_1110
